# xor-16/32 reduction steps in E1, norm and GLA output units via v_permlane16/32_swap instead of ds_bpermute
# baseline (speedup 1.0000x reference)
; __device__ __forceinline__ float bflo(unsigned w) { return __uint_as_float(w << 16); }
; __device__ __forceinline__ float bfhi(unsigned w) { return __uint_as_float(w & 0xffff0000u); }
; __device__ __forceinline__ unsigned cvt_pk_bf16(float lo, float hi) { unsigned r; asm volatile("v_cvt_pk_bf16_f32 %0, %1, %2" : "=v"(r) : "v"(lo), "v"(hi)); return r; }
; __device__ __forceinline__ void e1_row(CArgs& a, int l, int r, int lane, int dup, const E1Regs& g) {
;     ...
;     { const u32x4 w = g.cqw;
;         float x[8] = {bflo(w.x), bfhi(w.x), bflo(w.y), bfhi(w.y), bflo(w.z), bfhi(w.z), bflo(w.w), bfhi(w.w)};
;         float ss = 0.f;
; #pragma unroll
;         for (int e = 0; e < 8; ++e) ss += x[e] * x[e];
;         const float rs = rsqrtf(wave_sum(ss) * (1.f / 512.f) + EPS);
;         const float* gg = a.in[I_BQLN] + l * 512 + 8 * lane;
;         u32x4 o; o.x = cvt_pk_bf16(x[0] * rs * gg[0], x[1] * rs * gg[1]); o.y = cvt_pk_bf16(x[2] * rs * gg[2], x[3] * rs * gg[3]);
;         o.z = cvt_pk_bf16(x[4] * rs * gg[4], x[5] * rs * gg[5]); o.w = cvt_pk_bf16(x[6] * rs * gg[6], x[7] * rs * gg[7]); *((u32x4*)(P + C_BCQ) + lane) = o;
;     }
;     { const u32x2 w = g.ckw;
;         float x[4] = {bflo(w.x), bfhi(w.x), bflo(w.y), bfhi(w.y)};
;         const float rs = rsqrtf(wave_sum(x[0] * x[0] + x[1] * x[1] + x[2] * x[2] + x[3] * x[3]) * (1.f / 256.f) + EPS);
;         const float* gg = a.in[I_BKVLN] + l * 256 + 4 * lane;
;         u32x2 o; o.x = cvt_pk_bf16(x[0] * rs * gg[0], x[1] * rs * gg[1]); o.y = cvt_pk_bf16(x[2] * rs * gg[2], x[3] * rs * gg[3]); *((u32x2*)(P + C_BCKV) + lane) = o;
;     }
;     { const unsigned w = g.krw;
;         float x0 = lane < 32 ? bflo(w) : 0.f, x1 = lane < 32 ? bfhi(w) : 0.f;
;         const float rs = rsqrtf(wave_sum(x0 * x0 + x1 * x1) * (1.f / 64.f) + EPS);
;         const float* gg = a.in[I_BKRN] + l * 64 + 2 * (lane & 31);
;         float y0 = x0 * rs * gg[0], y1 = x1 * rs * gg[1];
;         if (lat) rope64(y0, y1, lane, prow, pcol);
;         if (lane < 32) *((unsigned*)(P + C_BKR) + lane) = cvt_pk_bf16(y0, y1);
;     }
.LBB0_50:
	s_or_b64 exec, exec, s[14:15]
	v_and_b32_e32 v27, 0xffff0000, v18
	v_lshlrev_b32_e32 v26, 16, v18
	v_mul_f32_e32 v30, v27, v27
	v_lshlrev_b32_e32 v28, 16, v19
	v_fmac_f32_e32 v30, v26, v26
	v_and_b32_e32 v29, 0xffff0000, v19
	v_fmac_f32_e32 v30, v28, v28
	v_and_b32_e32 v24, 0xffff0000, v20
	v_lshlrev_b32_e32 v25, 16, v20
	v_fmac_f32_e32 v30, v29, v29
	v_pk_mul_f32 v[18:19], v[24:25], v[24:25]
	s_mov_b64 s[4:5], 0x1000
	v_add_f32_e32 v19, v19, v30
	v_add_f32_e32 v30, v18, v19
	v_and_b32_e32 v18, 0xffff0000, v21
	v_lshlrev_b32_e32 v19, 16, v21
	v_pk_mul_f32 v[20:21], v[18:19], v[18:19]
	v_lshl_add_u64 v[22:23], v[58:59], 0, s[4:5]
	v_add_f32_e32 v21, v21, v30
	v_add_f32_e32 v20, v20, v21
	s_nop 1
	v_add_f32_dpp v20, v20, v20 quad_perm:[1,0,3,2] row_mask:0xf bank_mask:0xf
	s_nop 1
	v_add_f32_dpp v20, v20, v20 quad_perm:[2,3,0,1] row_mask:0xf bank_mask:0xf
	s_nop 1
	v_add_f32_dpp v20, v20, v20 row_half_mirror row_mask:0xf bank_mask:0xf
	s_nop 1
	v_add_f32_dpp v20, v20, v20 row_mirror row_mask:0xf bank_mask:0xf
	v_xor_b32_e32 v21, 16, v223
	v_cmp_lt_i32_e64 s[52:53], v21, v95
	s_nop 1
	v_cndmask_b32_e64 v21, v223, v21, s[52:53]
	v_lshlrev_b32_e32 v60, 2, v21
	v_mov_b32_e32 v21, v20
	s_nop 1
	v_permlane16_swap_b32_e32 v20, v21
	v_add_f32_e32 v20, v20, v21
	v_xor_b32_e32 v21, 32, v223
	v_cmp_lt_i32_e64 s[52:53], v21, v95
	s_nop 1
	v_cndmask_b32_e64 v21, v223, v21, s[52:53]
	v_lshlrev_b32_e32 v61, 2, v21
	v_mov_b32_e32 v21, v20
	s_nop 1
	v_permlane32_swap_b32_e32 v20, v21
	v_add_f32_e32 v20, v20, v21
	v_fmamk_f32 v20, v20, 0x3b000000, v216
	v_cmp_gt_f32_e64 s[52:53], s26, v20
	v_mul_f32_e32 v21, 0x4b800000, v20
	s_nop 0
	v_cndmask_b32_e64 v20, v20, v21, s[52:53]
	v_rsq_f32_e32 v20, v20
	s_nop 0
	v_mul_f32_e32 v21, 0x45800000, v20
	v_cndmask_b32_e64 v30, v20, v21, s[52:53]
	v_mov_b64_e32 v[20:21], v[126:127]
	v_mul_f32_e32 v26, v30, v26
	v_mul_f32_e32 v25, v30, v25
	v_mul_f32_e32 v24, v30, v24
	v_mul_f32_e32 v19, v30, v19
	v_mul_f32_e32 v18, v30, v18
	v_mul_f32_e32 v20, v20, v26
	v_mul_f32_e32 v26, v30, v27
	v_mul_f32_e32 v21, v21, v26
	v_cvt_pk_bf16_f32 v26, v20, v21
	v_mov_b64_e32 v[20:21], v[128:129]
	v_mul_f32_e32 v27, v30, v28
	v_mul_f32_e32 v20, v20, v27
	v_mul_f32_e32 v27, v30, v29
	v_mul_f32_e32 v21, v21, v27
	v_cvt_pk_bf16_f32 v27, v20, v21
	v_mov_b64_e32 v[20:21], v[130:131]
	v_mul_f32_e32 v20, v20, v25
	v_mul_f32_e32 v21, v21, v24
	v_cvt_pk_bf16_f32 v28, v20, v21
	v_mov_b64_e32 v[20:21], v[132:133]
	v_mul_f32_e32 v19, v19, v20
	v_mul_f32_e32 v18, v18, v21
	v_lshlrev_b32_e32 v20, 16, v56
	v_and_b32_e32 v21, 0xffff0000, v56
	v_cvt_pk_bf16_f32 v29, v19, v18
	v_pk_mul_f32 v[24:25], v[20:21], v[20:21]
	v_and_b32_e32 v18, 0xffff0000, v57
	v_lshlrev_b32_e32 v19, 16, v57
	global_store_dwordx4 v[54:55], v[26:29], off offset:3072
	s_nop 1
	v_add_f32_e32 v24, v24, v25
	s_nop 0
	v_pk_mul_f32 v[26:27], v[18:19], v[18:19]
	s_nop 0
	v_add_f32_e32 v24, v27, v24
	v_add_f32_e32 v24, v26, v24
	s_nop 1
	v_add_f32_dpp v24, v24, v24 quad_perm:[1,0,3,2] row_mask:0xf bank_mask:0xf
	s_nop 1
	v_add_f32_dpp v24, v24, v24 quad_perm:[2,3,0,1] row_mask:0xf bank_mask:0xf
	s_nop 1
	v_add_f32_dpp v24, v24, v24 row_half_mirror row_mask:0xf bank_mask:0xf
	s_nop 1
	v_add_f32_dpp v24, v24, v24 row_mirror row_mask:0xf bank_mask:0xf
	v_mov_b32_e32 v25, v24
	s_nop 1
	v_permlane16_swap_b32_e32 v24, v25
	v_add_f32_e32 v24, v24, v25
	v_mov_b32_e32 v25, v24
	s_nop 1
	v_permlane32_swap_b32_e32 v24, v25
	v_add_f32_e32 v24, v24, v25
	v_fmamk_f32 v24, v24, 0x3b800000, v216
	v_cmp_gt_f32_e64 s[52:53], s26, v24
	v_mul_f32_e32 v25, 0x4b800000, v24
	s_nop 0
	v_cndmask_b32_e64 v24, v24, v25, s[52:53]
	v_rsq_f32_e32 v24, v24
	s_nop 0
	v_mul_f32_e32 v25, 0x45800000, v24
	v_cndmask_b32_e64 v26, v24, v25, s[52:53]
	v_mov_b64_e32 v[24:25], v[134:135]
	v_mul_f32_e32 v20, v26, v20
	v_mul_f32_e32 v21, v26, v21
	v_mul_f32_e32 v19, v26, v19
	v_mul_f32_e32 v18, v26, v18
	v_mul_f32_e32 v20, v24, v20
	v_mul_f32_e32 v21, v25, v21
	v_cvt_pk_bf16_f32 v20, v20, v21
	v_mov_b64_e32 v[24:25], v[136:137]
	v_mul_f32_e32 v19, v24, v19
	v_mul_f32_e32 v18, v25, v18
	v_cvt_pk_bf16_f32 v21, v19, v18
	v_and_b32_e32 v19, 0xffff0000, v94
	global_store_dwordx2 v[22:23], v[20:21], off
	s_nop 1
	v_lshlrev_b32_e32 v18, 16, v94
	v_cndmask_b32_e64 v21, 0, v19, s[42:43]
	v_cndmask_b32_e64 v18, 0, v18, s[42:43]
	v_mul_f32_e32 v19, v21, v21
	v_fmac_f32_e32 v19, v18, v18
	s_nop 1
	v_add_f32_dpp v19, v19, v19 quad_perm:[1,0,3,2] row_mask:0xf bank_mask:0xf
	s_nop 1
	v_add_f32_dpp v19, v19, v19 quad_perm:[2,3,0,1] row_mask:0xf bank_mask:0xf
	s_nop 1
	v_add_f32_dpp v19, v19, v19 row_half_mirror row_mask:0xf bank_mask:0xf
	s_nop 1
	v_add_f32_dpp v19, v19, v19 row_mirror row_mask:0xf bank_mask:0xf
	v_mov_b32_e32 v20, v19
	s_nop 1
	v_permlane16_swap_b32_e32 v19, v20
	v_add_f32_e32 v19, v19, v20
	v_mov_b32_e32 v20, v19
	s_nop 1
	v_permlane32_swap_b32_e32 v19, v20
	v_add_f32_e32 v19, v19, v20
	v_fmamk_f32 v19, v19, 0x3c800000, v216
	v_cmp_gt_f32_e64 s[52:53], s26, v19
	v_mul_f32_e32 v20, 0x4b800000, v19
	s_nop 0
	v_cndmask_b32_e64 v19, v19, v20, s[52:53]
	v_rsq_f32_e32 v19, v19
	s_nop 0
	v_mul_f32_e32 v20, 0x45800000, v19
	v_cndmask_b32_e64 v20, v19, v20, s[52:53]
	v_mov_b32_e32 v19, v20
	v_pk_mul_f32 v[18:19], v[20:21], v[18:19]
	v_mov_b64_e32 v[20:21], v[138:139]
	v_pk_mul_f32 v[18:19], v[20:21], v[18:19]
	s_and_saveexec_b64 s[14:15], s[48:49]
	s_cbranch_execnz .LBB0_53
	s_or_b64 exec, exec, s[14:15]
	s_and_saveexec_b64 s[14:15], s[42:43]
	s_cbranch_execnz .LBB0_54

; __device__ __forceinline__ float bflo(unsigned w) { return __uint_as_float(w << 16); }
; __device__ __forceinline__ float bfhi(unsigned w) { return __uint_as_float(w & 0xffff0000u); }
; __device__ __forceinline__ unsigned cvt_pk_bf16(float lo, float hi) { unsigned r; asm volatile("v_cvt_pk_bf16_f32 %0, %1, %2" : "=v"(r) : "v"(lo), "v"(hi)); return r; }
; __device__ __forceinline__ void e1_row(CArgs& a, int l, int r, int lane, int dup, const E1Regs& g) {
;     ...
;     { const u32x4 w = g.cqw;
;         float x[8] = {bflo(w.x), bfhi(w.x), bflo(w.y), bfhi(w.y), bflo(w.z), bfhi(w.z), bflo(w.w), bfhi(w.w)};
;         float ss = 0.f;
; #pragma unroll
;         for (int e = 0; e < 8; ++e) ss += x[e] * x[e];
;         const float rs = rsqrtf(wave_sum(ss) * (1.f / 512.f) + EPS);
;         const float* gg = a.in[I_BQLN] + l * 512 + 8 * lane;
;         u32x4 o; o.x = cvt_pk_bf16(x[0] * rs * gg[0], x[1] * rs * gg[1]); o.y = cvt_pk_bf16(x[2] * rs * gg[2], x[3] * rs * gg[3]);
;         o.z = cvt_pk_bf16(x[4] * rs * gg[4], x[5] * rs * gg[5]); o.w = cvt_pk_bf16(x[6] * rs * gg[6], x[7] * rs * gg[7]); *((u32x4*)(P + C_BCQ) + lane) = o;
;     }
;     { const u32x2 w = g.ckw;
;         float x[4] = {bflo(w.x), bfhi(w.x), bflo(w.y), bfhi(w.y)};
;         const float rs = rsqrtf(wave_sum(x[0] * x[0] + x[1] * x[1] + x[2] * x[2] + x[3] * x[3]) * (1.f / 256.f) + EPS);
;         const float* gg = a.in[I_BKVLN] + l * 256 + 4 * lane;
;         u32x2 o; o.x = cvt_pk_bf16(x[0] * rs * gg[0], x[1] * rs * gg[1]); o.y = cvt_pk_bf16(x[2] * rs * gg[2], x[3] * rs * gg[3]); *((u32x2*)(P + C_BCKV) + lane) = o;
;     }
;     { const unsigned w = g.krw;
;         float x0 = lane < 32 ? bflo(w) : 0.f, x1 = lane < 32 ? bfhi(w) : 0.f;
;         const float rs = rsqrtf(wave_sum(x0 * x0 + x1 * x1) * (1.f / 64.f) + EPS);
;         const float* gg = a.in[I_BKRN] + l * 64 + 2 * (lane & 31);
;         float y0 = x0 * rs * gg[0], y1 = x1 * rs * gg[1];
;         if (lat) rope64(y0, y1, lane, prow, pcol);
;         if (lane < 32) *((unsigned*)(P + C_BKR) + lane) = cvt_pk_bf16(y0, y1);
;     }
.LBB0_65:
	s_or_b64 exec, exec, s[14:15]
	s_nop 0
	v_and_b32_e32 v8, 0xffff0000, v2
	v_lshlrev_b32_e32 v0, 16, v2
	v_mul_f32_e32 v11, v8, v8
	v_lshlrev_b32_e32 v9, 16, v3
	v_fmac_f32_e32 v11, v0, v0
	v_and_b32_e32 v10, 0xffff0000, v3
	v_fmac_f32_e32 v11, v9, v9
	v_and_b32_e32 v6, 0xffff0000, v4
	v_lshlrev_b32_e32 v7, 16, v4
	v_fmac_f32_e32 v11, v10, v10
	v_pk_mul_f32 v[2:3], v[6:7], v[6:7]
	v_mov_b32_e32 v49, v1
	v_add_f32_e32 v3, v3, v11
	v_add_f32_e32 v11, v2, v3
	v_and_b32_e32 v2, 0xffff0000, v5
	v_lshlrev_b32_e32 v3, 16, v5
	v_pk_mul_f32 v[4:5], v[2:3], v[2:3]
	s_nop 0
	v_add_f32_e32 v5, v5, v11
	v_add_f32_e32 v4, v4, v5
	s_nop 1
	v_add_f32_dpp v4, v4, v4 quad_perm:[1,0,3,2] row_mask:0xf bank_mask:0xf
	s_nop 1
	v_add_f32_dpp v4, v4, v4 quad_perm:[2,3,0,1] row_mask:0xf bank_mask:0xf
	s_nop 1
	v_add_f32_dpp v4, v4, v4 row_half_mirror row_mask:0xf bank_mask:0xf
	s_nop 1
	v_add_f32_dpp v4, v4, v4 row_mirror row_mask:0xf bank_mask:0xf
	v_mov_b32_e32 v5, v4
	s_nop 1
	v_permlane16_swap_b32_e32 v4, v5
	v_add_f32_e32 v4, v4, v5
	v_mov_b32_e32 v5, v4
	s_nop 1
	v_permlane32_swap_b32_e32 v4, v5
	v_add_f32_e32 v4, v4, v5
	v_fmamk_f32 v4, v4, 0x3b000000, v216
	v_cmp_gt_f32_e64 s[48:49], s26, v4
	v_mul_f32_e32 v5, 0x4b800000, v4
	s_nop 0
	v_cndmask_b32_e64 v4, v4, v5, s[48:49]
	v_rsq_f32_e32 v4, v4
	s_nop 0
	v_mul_f32_e32 v5, 0x45800000, v4
	v_cndmask_b32_e64 v11, v4, v5, s[48:49]
	v_mov_b64_e32 v[4:5], v[126:127]
	v_mul_f32_e32 v0, v11, v0
	v_mul_f32_e32 v6, v11, v6
	v_mul_f32_e32 v2, v11, v2
	v_mul_f32_e32 v0, v4, v0
	v_mul_f32_e32 v4, v11, v8
	v_mul_f32_e32 v4, v5, v4
	v_cvt_pk_bf16_f32 v4, v0, v4
	v_mul_f32_e32 v0, v11, v9
	v_mov_b64_e32 v[8:9], v[128:129]
	v_mul_f32_e32 v5, v11, v10
	v_mul_f32_e32 v5, v9, v5
	v_mul_f32_e32 v0, v8, v0
	v_cvt_pk_bf16_f32 v5, v0, v5
	v_mov_b64_e32 v[8:9], v[130:131]
	v_mul_f32_e32 v0, v11, v7
	v_mul_f32_e32 v6, v9, v6
	v_mul_f32_e32 v0, v8, v0
	v_cvt_pk_bf16_f32 v6, v0, v6
	v_mov_b64_e32 v[8:9], v[132:133]
	v_mul_f32_e32 v0, v11, v3
	v_lshlrev_b32_e32 v3, 16, v51
	v_mul_f32_e32 v0, v0, v8
	v_mul_f32_e32 v2, v2, v9
	v_cvt_pk_bf16_f32 v7, v0, v2
	global_store_dwordx4 v[16:17], v[4:7], off offset:3072
	s_nop 1
	v_and_b32_e32 v2, 0xffff0000, v51
	v_pk_mul_f32 v[8:9], v[2:3], v[2:3]
	v_lshlrev_b32_e32 v4, 16, v50
	v_and_b32_e32 v5, 0xffff0000, v50
	v_pk_mul_f32 v[6:7], v[4:5], v[4:5]
	s_nop 0
	v_add_f32_e32 v0, v6, v7
	v_add_f32_e32 v0, v9, v0
	v_add_f32_e32 v0, v8, v0
	s_nop 1
	v_add_f32_dpp v0, v0, v0 quad_perm:[1,0,3,2] row_mask:0xf bank_mask:0xf
	s_nop 1
	v_add_f32_dpp v0, v0, v0 quad_perm:[2,3,0,1] row_mask:0xf bank_mask:0xf
	s_nop 1
	v_add_f32_dpp v0, v0, v0 row_half_mirror row_mask:0xf bank_mask:0xf
	s_nop 1
	v_add_f32_dpp v0, v0, v0 row_mirror row_mask:0xf bank_mask:0xf
	v_mov_b32_e32 v6, v0
	s_nop 1
	v_permlane16_swap_b32_e32 v0, v6
	v_add_f32_e32 v0, v0, v6
	v_mov_b32_e32 v6, v0
	s_nop 1
	v_permlane32_swap_b32_e32 v0, v6
	v_add_f32_e32 v0, v0, v6
	v_fmamk_f32 v0, v0, 0x3b800000, v216
	v_cmp_gt_f32_e64 s[48:49], s26, v0
	v_mul_f32_e32 v6, 0x4b800000, v0
	s_nop 0
	v_cndmask_b32_e64 v0, v0, v6, s[48:49]
	v_rsq_f32_e32 v0, v0
	s_nop 0
	v_mul_f32_e32 v6, 0x45800000, v0
	v_cndmask_b32_e64 v0, v0, v6, s[48:49]
	v_mov_b64_e32 v[6:7], v[134:135]
	v_mul_f32_e32 v4, v0, v4
	v_mul_f32_e32 v5, v0, v5
	v_mul_f32_e32 v3, v0, v3
	v_mul_f32_e32 v0, v0, v2
	v_mul_f32_e32 v4, v6, v4
	v_mul_f32_e32 v5, v7, v5
	v_cvt_pk_bf16_f32 v4, v4, v5
	v_mov_b64_e32 v[6:7], v[136:137]
	v_mul_f32_e32 v3, v6, v3
	v_mul_f32_e32 v0, v7, v0
	v_cvt_pk_bf16_f32 v5, v3, v0
	v_lshl_add_u64 v[2:3], v[14:15], 0, v[48:49]
	v_add_co_u32_e64 v2, s[48:49], s10, v2
	v_lshlrev_b32_e32 v0, 16, v90
	s_nop 0
	v_addc_co_u32_e64 v3, s[48:49], 0, v3, s[48:49]
	global_store_dwordx2 v[2:3], v[4:5], off
	s_nop 1
	v_and_b32_e32 v3, 0xffff0000, v90
	v_cndmask_b32_e64 v5, 0, v3, s[42:43]
	v_cndmask_b32_e64 v2, 0, v0, s[42:43]
	v_mul_f32_e32 v0, v5, v5
	v_fmac_f32_e32 v0, v2, v2
	s_nop 1
	v_add_f32_dpp v0, v0, v0 quad_perm:[1,0,3,2] row_mask:0xf bank_mask:0xf
	s_nop 1
	v_add_f32_dpp v0, v0, v0 quad_perm:[2,3,0,1] row_mask:0xf bank_mask:0xf
	s_nop 1
	v_add_f32_dpp v0, v0, v0 row_half_mirror row_mask:0xf bank_mask:0xf
	s_nop 1
	v_add_f32_dpp v0, v0, v0 row_mirror row_mask:0xf bank_mask:0xf
	v_mov_b32_e32 v3, v0
	s_nop 1
	v_permlane16_swap_b32_e32 v0, v3
	v_add_f32_e32 v0, v0, v3
	v_mov_b32_e32 v3, v0
	s_nop 1
	v_permlane32_swap_b32_e32 v0, v3
	v_add_f32_e32 v0, v0, v3
	v_fmamk_f32 v0, v0, 0x3c800000, v216
	v_cmp_gt_f32_e64 s[48:49], s26, v0
	v_mul_f32_e32 v3, 0x4b800000, v0
	s_nop 0
	v_cndmask_b32_e64 v0, v0, v3, s[48:49]
	v_rsq_f32_e32 v0, v0
	s_nop 0
	v_mul_f32_e32 v3, 0x45800000, v0
	v_cndmask_b32_e64 v4, v0, v3, s[48:49]
	v_mov_b32_e32 v3, v4
	v_pk_mul_f32 v[2:3], v[4:5], v[2:3]
	v_mov_b64_e32 v[4:5], v[138:139]
	v_pk_mul_f32 v[2:3], v[4:5], v[2:3]
	s_and_saveexec_b64 s[14:15], vcc
	s_cbranch_execz .LBB0_67
	v_cndmask_b32_e64 v0, v63, v62, s[44:45]
	v_cvt_f32_i32_e32 v0, v0
	ds_bpermute_b32 v4, v45, v2
	v_mul_f32_e32 v5, v88, v0
	v_mul_f32_e32 v0, v89, v0
	v_mul_f32_e32 v8, 0.15915494, v5
	v_mul_f32_e32 v0, 0.15915494, v0
	ds_bpermute_b32 v5, v45, v3
	v_sin_f32_e32 v6, v8
	v_sin_f32_e32 v7, v0
	v_cos_f32_e32 v8, v8
	v_cos_f32_e32 v9, v0
	s_waitcnt lgkmcnt(0)
	v_pk_mul_f32 v[4:5], v[6:7], v[4:5]
	s_nop 0
	v_cndmask_b32_e64 v5, v5, -v5, s[46:47]
	v_cndmask_b32_e64 v4, v4, -v4, s[46:47]
	v_pk_fma_f32 v[2:3], v[8:9], v[2:3], v[4:5]

; #define LAS __attribute__((address_space(3)))
; __device__ __forceinline__ int crow16(int r, int hi) { return (r & 3) + 8 * (r >> 2) + 4 * hi; }
; __device__ __forceinline__ void gla_p3(CArgs& a, int l, int cc, int h, LAS float* L) {
;     ...
;     { const int ib = wid >> 2, eb = wid & 3; f32x16 acc = {};
; #pragma unroll
;       for (int ks = 0; ks < 4; ++ks) {
;           acc = __builtin_amdgcn_mfma_f32_32x32x16_bf16(ldfrag(B + GB_ATT, 32 * ib + r32, ks, hi), ldfrag(B + GB_VT, 32 * eb + r32, ks, hi), acc, 0, 0, 0);
;           acc = __builtin_amdgcn_mfma_f32_32x32x16_bf16(ldfrag(B + GB_QDF, 32 * ib + r32, ks, hi), ldfrag(B + GB_SFT, 32 * eb + r32, ks, hi), acc, 0, 0, 0);
;           acc = __builtin_amdgcn_mfma_f32_32x32x16_bf16(ldfrag(B + GB_QDB, 32 * ib + r32, ks, hi), ldfrag(B + GB_SBT, 32 * eb + r32, ks, hi), acc, 0, 0, 0); }
; #pragma unroll
;       for (int r = 0; r < 16; ++r) L[(32 * ib + crow16(r, hi)) * 128 + 32 * eb + r32] = acc[r]; }
;     __syncthreads();
;     const int i0 = (tid >> 5) * 4, e4 = (tid & 31) * 4;
;     bf16_t* Z = (bf16_t*)(a.ws + WS_HZ);
;     const f32x4 gn = *(const f32x4*)(a.in[I_CON] + l * 128 + e4);
; #pragma unroll
;     for (int r = 0; r < 4; ++r) { const f32x4 o = *(const LAS f32x4*)(L + (i0 + r) * 128 + e4);
;         float ss = (o.x * o.x + o.y * o.y) + (o.z * o.z + o.w * o.w);
; #pragma unroll
;         for (int m = 1; m < 32; m <<= 1) ss += __shfl_xor(ss, m);
;         const float rs = rsqrtf(ss * (1.f / 128.f) + EPS);
;         const size_t row = (size_t)cc * 64 + i0 + r;
;         const u32x2 gw = *(const u32x2*)(P + (size_t)(i0 + r) * INP + C_CG + h * 128 + e4);
;         const f32x4 y = o * rs * gn;
.LBB0_96:
	s_or_b64 exec, exec, s[42:43]
	v_ashrrev_i32_e32 v38, 8, v34
	v_lshl_or_b32 v2, v38, 5, v36
	s_movk_i32 s5, 0x90
	v_mul_lo_u32 v10, v2, s5
	s_add_i32 s5, 0, 0x15a00
	v_add3_u32 v30, s5, v10, v37
	s_waitcnt lgkmcnt(0)
	s_barrier
	v_bfe_u32 v39, v34, 6, 2
	ds_read_b128 v[2:5], v30
	v_lshl_or_b32 v6, v39, 5, v36
	v_mul_u32_u24_e32 v31, 0x90, v6
	v_add3_u32 v40, s17, v31, v37
	ds_read_b128 v[6:9], v40
	v_add3_u32 v41, 0, v10, v37
	ds_read_b128 v[18:21], v41 offset:33280
	s_waitcnt lgkmcnt(1)
	v_mfma_f32_32x32x16_bf16 v[2:17], v[2:5], v[6:9], 0
	s_add_i32 s5, 0, 0x17e00
	v_add3_u32 v42, s5, v31, v37
	ds_read_b128 v[22:25], v42
	ds_read_b128 v[26:29], v41 offset:42496
	s_add_i32 s5, 0, 0x1c600
	v_add3_u32 v37, s5, v31, v37
	v_and_b32_e32 v0, 0x7c, v0
	s_lshl_b32 s18, s4, 1
	s_waitcnt lgkmcnt(1)
	v_mfma_f32_32x32x16_bf16 v[2:17], v[18:21], v[22:25], v[2:17]
	ds_read_b128 v[18:21], v37
	s_ashr_i32 s23, s22, 31
	s_lshl_b64 s[4:5], s[22:23], 18
	s_add_u32 s4, s56, s4
	s_addc_u32 s5, s57, s5
	s_waitcnt lgkmcnt(0)
	v_mfma_f32_32x32x16_bf16 v[2:17], v[26:29], v[18:21], v[2:17]
	ds_read_b128 v[18:21], v30 offset:32
	ds_read_b128 v[22:25], v40 offset:32
	s_waitcnt lgkmcnt(0)
	v_mfma_f32_32x32x16_bf16 v[2:17], v[18:21], v[22:25], v[2:17]
	ds_read_b128 v[18:21], v41 offset:33312
	ds_read_b128 v[22:25], v42 offset:32
	s_waitcnt lgkmcnt(0)
	v_mfma_f32_32x32x16_bf16 v[2:17], v[18:21], v[22:25], v[2:17]
	ds_read_b128 v[18:21], v41 offset:42528
	ds_read_b128 v[22:25], v37 offset:32
	s_waitcnt lgkmcnt(0)
	v_mfma_f32_32x32x16_bf16 v[2:17], v[18:21], v[22:25], v[2:17]
	ds_read_b128 v[18:21], v30 offset:64
	ds_read_b128 v[22:25], v40 offset:64
	s_waitcnt lgkmcnt(0)
	v_mfma_f32_32x32x16_bf16 v[2:17], v[18:21], v[22:25], v[2:17]
	ds_read_b128 v[18:21], v41 offset:33344
	ds_read_b128 v[22:25], v42 offset:64
	s_waitcnt lgkmcnt(0)
	v_mfma_f32_32x32x16_bf16 v[2:17], v[18:21], v[22:25], v[2:17]
	ds_read_b128 v[22:25], v41 offset:42560
	ds_read_b128 v[26:29], v37 offset:64
	ds_read_b128 v[30:33], v30 offset:96
	v_lshlrev_b32_e32 v19, 11, v35
	v_ashrrev_i32_e32 v20, 3, v34
	v_lshlrev_b32_e32 v34, 14, v38
	v_lshlrev_b32_e32 v21, 2, v36
	v_lshlrev_b32_e32 v35, 7, v39
	s_waitcnt lgkmcnt(1)
	v_mfma_f32_32x32x16_bf16 v[2:17], v[22:25], v[26:29], v[2:17]
	ds_read_b128 v[22:25], v40 offset:96
	ds_read_b128 v[26:29], v41 offset:33376
	v_and_b32_e32 v18, -4, v20
	v_lshlrev_b32_e32 v36, 2, v0
	v_lshlrev_b32_e32 v0, 1, v0
	s_waitcnt lgkmcnt(1)
	v_mfma_f32_32x32x16_bf16 v[2:17], v[30:33], v[22:25], v[2:17]
	ds_read_b128 v[22:25], v42 offset:96
	v_add3_u32 v30, 0, v34, v19
	v_add3_u32 v21, v30, v35, v21
	ds_read_b128 v[30:33], v41 offset:42592
	v_ashrrev_i32_e32 v19, 31, v18
	s_waitcnt lgkmcnt(1)
	v_mfma_f32_32x32x16_bf16 v[2:17], v[26:29], v[22:25], v[2:17]
	ds_read_b128 v[22:25], v37 offset:96
	v_lshlrev_b64 v[26:27], 13, v[18:19]
	v_lshl_add_u64 v[26:27], s[20:21], 0, v[26:27]
	v_lshl_add_u64 v[26:27], v[26:27], 0, s[18:19]
	v_lshl_add_u64 v[26:27], v[26:27], 0, v[0:1]
	v_add_co_u32_e32 v26, vcc, s10, v26
	s_waitcnt lgkmcnt(0)
	v_mfma_f32_32x32x16_bf16 v[2:17], v[30:33], v[22:25], v[2:17]
	v_addc_co_u32_e32 v27, vcc, 0, v27, vcc
	s_nop 10
	ds_write2st64_b32 v21, v2, v3 offset1:2
	ds_write2st64_b32 v21, v4, v5 offset0:4 offset1:6
	ds_write2st64_b32 v21, v6, v7 offset0:16 offset1:18
	ds_write2st64_b32 v21, v8, v9 offset0:20 offset1:22
	ds_write2st64_b32 v21, v10, v11 offset0:32 offset1:34
	ds_write2st64_b32 v21, v12, v13 offset0:36 offset1:38
	ds_write2st64_b32 v21, v14, v15 offset0:48 offset1:50
	ds_write2st64_b32 v21, v16, v17 offset0:52 offset1:54
	s_waitcnt lgkmcnt(0)
	s_barrier
	global_load_dwordx2 v[10:11], v[26:27], off offset:2688
	global_load_dwordx4 v[2:5], v36, s[52:53]
	v_add_co_u32_e32 v76, vcc, 0x2000, v26
	s_nop 1
	v_addc_co_u32_e32 v77, vcc, 0, v27, vcc
	global_load_dwordx2 v[80:81], v[76:77], off offset:2688
	v_add_co_u32_e32 v76, vcc, 0x2000, v76
	s_nop 1
	v_addc_co_u32_e32 v77, vcc, 0, v77, vcc
	global_load_dwordx2 v[82:83], v[76:77], off offset:2688
	v_add_co_u32_e32 v76, vcc, 0x2000, v76
	s_nop 1
	v_addc_co_u32_e32 v77, vcc, 0, v77, vcc
	global_load_dwordx2 v[84:85], v[76:77], off offset:2688
	v_add_u32_e32 v22, 0, v36
	v_lshl_add_u32 v6, v18, 9, v22
	ds_read_b128 v[6:9], v6
	v_and_b32_e32 v12, 64, v223
	v_xor_b32_e32 v13, 1, v223
	v_add_u32_e32 v25, 64, v12
	v_cmp_lt_i32_e32 vcc, v13, v25
	s_waitcnt lgkmcnt(0)
	v_pk_mul_f32 v[14:15], v[6:7], v[6:7]
	v_xor_b32_e32 v23, 2, v223
	v_cndmask_b32_e32 v12, v223, v13, vcc
	v_lshlrev_b32_e32 v21, 2, v12
	v_pk_mul_f32 v[12:13], v[8:9], v[8:9]
	v_cmp_lt_i32_e32 vcc, v23, v25
	v_pk_mov_b32 v[16:17], v[14:15], v[12:13] op_sel:[1,0]
	v_mov_b32_e32 v15, v13
	v_pk_add_f32 v[12:13], v[16:17], v[14:15]
	v_cndmask_b32_e32 v15, v223, v23, vcc
	v_add_f32_e32 v12, v12, v13
	ds_bpermute_b32 v13, v21, v12
	v_lshlrev_b32_e32 v23, 2, v15
	v_xor_b32_e32 v24, 4, v223
	v_cmp_lt_i32_e32 vcc, v24, v25
	v_xor_b32_e32 v14, 8, v223
	s_waitcnt lgkmcnt(0)
	v_add_f32_e32 v12, v12, v13
	ds_bpermute_b32 v13, v23, v12
	v_cndmask_b32_e32 v16, v223, v24, vcc
	v_lshlrev_b32_e32 v24, 2, v16
	v_cmp_lt_i32_e64 s[40:41], v14, v25
	v_xor_b32_e32 v15, 16, v223
	s_waitcnt lgkmcnt(0)
	v_add_f32_e32 v12, v12, v13
	s_nop 1
	v_cndmask_b32_e64 v14, v223, v14, s[40:41]
	v_cmp_lt_i32_e32 vcc, v15, v25
	v_lshlrev_b32_e32 v25, 2, v14
	v_add_f32_dpp v14, v12, v12 row_half_mirror row_mask:0xf bank_mask:0xf
	ds_bpermute_b32 v16, v25, v14
	v_cndmask_b32_e32 v15, v223, v15, vcc
	v_lshlrev_b32_e32 v26, 2, v15
	v_or_b32_e32 v12, 1, v18
	v_ashrrev_i32_e32 v13, 31, v12
	s_waitcnt lgkmcnt(0)
; #define LAS __attribute__((address_space(3)))
; __device__ __forceinline__ float bflo(unsigned w) { return __uint_as_float(w << 16); }
; __device__ __forceinline__ float bfhi(unsigned w) { return __uint_as_float(w & 0xffff0000u); }
; __device__ __forceinline__ unsigned cvt_pk_bf16(float lo, float hi) { unsigned r; asm volatile("v_cvt_pk_bf16_f32 %0, %1, %2" : "=v"(r) : "v"(lo), "v"(hi)); return r; }
; __device__ __forceinline__ float silu_f(float g) { return g * __builtin_amdgcn_rcpf(1.f + __expf(-g)); }
; __device__ __forceinline__ void gla_p3(CArgs& a, int l, int cc, int h, LAS float* L) {
;     ...
;     for (int r = 0; r < 4; ++r) { const f32x4 o = *(const LAS f32x4*)(L + (i0 + r) * 128 + e4);
;         float ss = (o.x * o.x + o.y * o.y) + (o.z * o.z + o.w * o.w);
; #pragma unroll
;         for (int m = 1; m < 32; m <<= 1) ss += __shfl_xor(ss, m);
;         const float rs = rsqrtf(ss * (1.f / 128.f) + EPS);
;         const size_t row = (size_t)cc * 64 + i0 + r;
;         const u32x2 gw = *(const u32x2*)(P + (size_t)(i0 + r) * INP + C_CG + h * 128 + e4);
;         const f32x4 y = o * rs * gn;
;         u32x2 w; w.x = cvt_pk_bf16(y.x * silu_f(bflo(gw.x)), y.y * silu_f(bfhi(gw.x))); w.y = cvt_pk_bf16(y.z * silu_f(bflo(gw.y)), y.w * silu_f(bfhi(gw.y)));
;         *(u32x2*)(Z + row * DM + 1536 + h * 128 + e4) = w; }
	v_add_f32_e32 v16, v14, v16
	ds_bpermute_b32 v17, v26, v16
	v_lshlrev_b64 v[14:15], 13, v[12:13]
	v_lshl_add_u64 v[14:15], s[20:21], 0, v[14:15]
	v_lshl_add_u64 v[14:15], v[14:15], 0, s[18:19]
	v_lshl_add_u64 v[14:15], v[14:15], 0, v[0:1]
	s_waitcnt lgkmcnt(0)
	v_add_f32_e32 v13, v16, v17
	v_fmamk_f32 v13, v13, 0x3c000000, v216
	v_cmp_gt_f32_e32 vcc, s26, v13
	v_mul_f32_e32 v16, 0x4b800000, v13
	s_nop 0
	v_cndmask_b32_e32 v13, v13, v16, vcc
	v_rsq_f32_e32 v13, v13
	v_add_co_u32_e64 v16, s[40:41], s10, v14
	v_mul_f32_e32 v14, 0x45800000, v13
	v_cndmask_b32_e32 v14, v13, v14, vcc
	v_pk_mul_f32 v[6:7], v[6:7], v[14:15] op_sel_hi:[1,0]
	v_pk_mul_f32 v[8:9], v[8:9], v[14:15] op_sel_hi:[1,0]
	v_addc_co_u32_e64 v17, s[40:41], 0, v15, s[40:41]
	s_waitcnt vmcnt(1)
	v_lshlrev_b32_e32 v13, 16, v10
	v_and_b32_e32 v10, 0xffff0000, v10
	v_lshlrev_b32_e32 v14, 16, v11
	v_and_b32_e32 v11, 0xffff0000, v11
	v_mul_f32_e32 v15, 0xbfb8aa3b, v13
	v_mul_f32_e32 v27, 0xbfb8aa3b, v10
	v_mul_f32_e32 v28, 0xbfb8aa3b, v14
	v_mul_f32_e32 v29, 0xbfb8aa3b, v11
	v_exp_f32_e32 v15, v15
	v_exp_f32_e32 v27, v27
	v_exp_f32_e32 v28, v28
	v_exp_f32_e32 v29, v29
	v_add_f32_e32 v15, 1.0, v15
	v_add_f32_e32 v27, 1.0, v27
	v_add_f32_e32 v28, 1.0, v28
	v_add_f32_e32 v29, 1.0, v29
	v_rcp_f32_e32 v15, v15
	v_rcp_f32_e32 v27, v27
	v_rcp_f32_e32 v28, v28
	v_rcp_f32_e32 v29, v29
	s_waitcnt vmcnt(0)
	v_pk_mul_f32 v[8:9], v[4:5], v[8:9]
	v_pk_mul_f32 v[6:7], v[2:3], v[6:7]
	v_mul_f32_e32 v13, v15, v13
	v_mul_f32_e32 v10, v27, v10
	v_mul_f32_e32 v14, v28, v14
	v_mul_f32_e32 v11, v29, v11
	v_mul_f32_e32 v6, v13, v6
	v_mul_f32_e32 v7, v10, v7
	v_mul_f32_e32 v8, v14, v8
	v_mul_f32_e32 v9, v11, v9
	v_cvt_pk_bf16_f32 v14, v6, v7
	v_cvt_pk_bf16_f32 v15, v8, v9
	v_mov_b64_e32 v[16:17], v[80:81]
	v_lshl_add_u32 v6, v12, 9, v22
	ds_read_b128 v[6:9], v6
	s_waitcnt lgkmcnt(0)
	v_pk_mul_f32 v[10:11], v[8:9], v[8:9]
	v_pk_mul_f32 v[12:13], v[6:7], v[6:7]
	s_nop 0
	v_pk_mov_b32 v[28:29], v[12:13], v[10:11] op_sel:[1,0]
	v_mov_b32_e32 v13, v11
	v_pk_add_f32 v[10:11], v[28:29], v[12:13]
	v_or_b32_e32 v12, 2, v18
	v_add_f32_e32 v10, v10, v11
	s_nop 1
	v_ashrrev_i32_e32 v13, 31, v12
	v_add_f32_dpp v27, v10, v10 quad_perm:[1,0,3,2] row_mask:0xf bank_mask:0xf
	ds_bpermute_b32 v28, v23, v27
	v_lshlrev_b64 v[10:11], 12, v[18:19]
	v_lshlrev_b64 v[18:19], 13, v[12:13]
	v_lshl_add_u64 v[10:11], s[4:5], 0, v[10:11]
	v_lshl_add_u64 v[10:11], v[10:11], 0, s[18:19]
	s_waitcnt lgkmcnt(0)
	v_add_f32_e32 v27, v27, v28
	ds_bpermute_b32 v28, v24, v27
	v_lshl_add_u64 v[10:11], v[10:11], 0, v[0:1]
	s_mov_b32 s4, 0xb900000
	v_lshl_add_u64 v[18:19], s[20:21], 0, v[18:19]
	v_lshl_add_u64 v[18:19], v[18:19], 0, s[18:19]
	s_waitcnt lgkmcnt(0)
	v_add_f32_e32 v13, v27, v28
	ds_bpermute_b32 v27, v25, v13
	v_add_co_u32_e32 v28, vcc, s4, v10
	v_lshl_add_u64 v[18:19], v[18:19], 0, v[0:1]
	s_nop 0
	v_addc_co_u32_e32 v29, vcc, 0, v11, vcc
	s_waitcnt lgkmcnt(0)
	v_add_f32_e32 v13, v13, v27
	v_mov_b32_e32 v27, v13
	global_store_dwordx2 v[28:29], v[14:15], off offset:3072
	v_add_co_u32_e32 v18, vcc, s10, v18
	s_mov_b32 s4, 0xb901000
	s_nop 1
	v_permlane16_swap_b32_e32 v13, v27
	v_add_f32_e32 v13, v13, v27
	v_fmamk_f32 v13, v13, 0x3c000000, v216
	v_cmp_gt_f32_e64 s[40:41], s26, v13
	v_mul_f32_e32 v27, 0x4b800000, v13
	v_addc_co_u32_e32 v19, vcc, 0, v19, vcc
	v_cndmask_b32_e64 v13, v13, v27, s[40:41]
	v_rsq_f32_e32 v13, v13
	s_nop 0
	v_mul_f32_e32 v14, 0x45800000, v13
	v_cndmask_b32_e64 v14, v13, v14, s[40:41]
	v_pk_mul_f32 v[6:7], v[6:7], v[14:15] op_sel_hi:[1,0]
	v_pk_mul_f32 v[8:9], v[8:9], v[14:15] op_sel_hi:[1,0]
	v_pk_mul_f32 v[6:7], v[2:3], v[6:7]
	v_pk_mul_f32 v[8:9], v[4:5], v[8:9]
	s_waitcnt vmcnt(1)
	v_lshlrev_b32_e32 v13, 16, v16
	v_and_b32_e32 v14, 0xffff0000, v16
	v_and_b32_e32 v16, 0xffff0000, v17
	v_lshlrev_b32_e32 v15, 16, v17
	v_mul_f32_e32 v29, 0xbfb8aa3b, v16
	v_mul_f32_e32 v17, 0xbfb8aa3b, v13
	v_mul_f32_e32 v27, 0xbfb8aa3b, v14
	v_mul_f32_e32 v28, 0xbfb8aa3b, v15
	v_exp_f32_e32 v29, v29
	v_exp_f32_e32 v17, v17
	v_exp_f32_e32 v27, v27
	v_exp_f32_e32 v28, v28
	v_add_f32_e32 v29, 1.0, v29
	v_add_f32_e32 v17, 1.0, v17
	v_add_f32_e32 v27, 1.0, v27
	v_add_f32_e32 v28, 1.0, v28
	v_rcp_f32_e32 v29, v29
	v_rcp_f32_e32 v17, v17
	v_rcp_f32_e32 v27, v27
	v_rcp_f32_e32 v28, v28
	v_mul_f32_e32 v16, v29, v16
	v_mul_f32_e32 v13, v17, v13
	v_mul_f32_e32 v14, v27, v14
	v_mul_f32_e32 v15, v28, v15
	v_mul_f32_e32 v9, v16, v9
	v_mul_f32_e32 v6, v13, v6
	v_mul_f32_e32 v7, v14, v7
	v_mul_f32_e32 v13, v15, v8
	v_cvt_pk_bf16_f32 v8, v6, v7
	v_cvt_pk_bf16_f32 v9, v13, v9
	v_mov_b64_e32 v[16:17], v[82:83]
	v_lshl_add_u32 v6, v12, 9, v22
	ds_read_b128 v[12:15], v6
	s_waitcnt lgkmcnt(0)
; #define LAS __attribute__((address_space(3)))
; __device__ __forceinline__ float bflo(unsigned w) { return __uint_as_float(w << 16); }
; __device__ __forceinline__ float bfhi(unsigned w) { return __uint_as_float(w & 0xffff0000u); }
; __device__ __forceinline__ unsigned cvt_pk_bf16(float lo, float hi) { unsigned r; asm volatile("v_cvt_pk_bf16_f32 %0, %1, %2" : "=v"(r) : "v"(lo), "v"(hi)); return r; }
; __device__ __forceinline__ float silu_f(float g) { return g * __builtin_amdgcn_rcpf(1.f + __expf(-g)); }
; __device__ __forceinline__ void gla_p3(CArgs& a, int l, int cc, int h, LAS float* L) {
;     ...
;     for (int r = 0; r < 4; ++r) { const f32x4 o = *(const LAS f32x4*)(L + (i0 + r) * 128 + e4);
;         float ss = (o.x * o.x + o.y * o.y) + (o.z * o.z + o.w * o.w);
; #pragma unroll
;         for (int m = 1; m < 32; m <<= 1) ss += __shfl_xor(ss, m);
;         const float rs = rsqrtf(ss * (1.f / 128.f) + EPS);
;         const size_t row = (size_t)cc * 64 + i0 + r;
;         const u32x2 gw = *(const u32x2*)(P + (size_t)(i0 + r) * INP + C_CG + h * 128 + e4);
;         const f32x4 y = o * rs * gn;
;         u32x2 w; w.x = cvt_pk_bf16(y.x * silu_f(bflo(gw.x)), y.y * silu_f(bfhi(gw.x))); w.y = cvt_pk_bf16(y.z * silu_f(bflo(gw.y)), y.w * silu_f(bfhi(gw.y)));
;         *(u32x2*)(Z + row * DM + 1536 + h * 128 + e4) = w; }
	v_pk_mul_f32 v[6:7], v[14:15], v[14:15]
	v_pk_mul_f32 v[18:19], v[12:13], v[12:13]
	s_nop 0
	v_pk_mov_b32 v[28:29], v[18:19], v[6:7] op_sel:[1,0]
	v_mov_b32_e32 v19, v7
	v_pk_add_f32 v[6:7], v[28:29], v[18:19]
	s_nop 0
	v_add_f32_e32 v6, v6, v7
	s_nop 1
	v_add_f32_dpp v6, v6, v6 quad_perm:[1,0,3,2] row_mask:0xf bank_mask:0xf
	s_nop 1
	v_add_f32_dpp v27, v6, v6 quad_perm:[2,3,0,1] row_mask:0xf bank_mask:0xf
	ds_bpermute_b32 v28, v24, v27
	v_or_b32_e32 v6, 3, v20
	v_ashrrev_i32_e32 v7, 31, v6
	v_lshlrev_b64 v[18:19], 13, v[6:7]
	v_lshl_add_u64 v[18:19], s[20:21], 0, v[18:19]
	s_waitcnt lgkmcnt(0)
	v_add_f32_e32 v7, v27, v28
	s_nop 1
	v_lshl_add_u64 v[18:19], v[18:19], 0, s[18:19]
	v_lshl_add_u64 v[18:19], v[18:19], 0, v[0:1]
	v_add_co_u32_e32 v28, vcc, s4, v10
	v_add_f32_dpp v0, v7, v7 row_mirror row_mask:0xf bank_mask:0xf
	v_mov_b32_e32 v7, v0
	v_addc_co_u32_e32 v29, vcc, 0, v11, vcc
	global_store_dwordx2 v[28:29], v[8:9], off offset:3072
	v_add_co_u32_e64 v18, s[40:41], s10, v18
	s_nop 1
	v_permlane16_swap_b32_e32 v0, v7
	v_add_f32_e32 v0, v0, v7
	v_fmamk_f32 v0, v0, 0x3c000000, v216
	v_cmp_gt_f32_e32 vcc, s26, v0
	v_mul_f32_e32 v7, 0x4b800000, v0
	v_addc_co_u32_e64 v19, s[40:41], 0, v19, s[40:41]
	v_cndmask_b32_e32 v0, v0, v7, vcc
	v_rsq_f32_e32 v0, v0
	s_mov_b32 s4, 0xb902000
	v_mul_f32_e32 v7, 0x45800000, v0
	v_cndmask_b32_e32 v0, v0, v7, vcc
	v_pk_mul_f32 v[8:9], v[12:13], v[0:1] op_sel_hi:[1,0]
	v_pk_mul_f32 v[12:13], v[14:15], v[0:1] op_sel_hi:[1,0]
	v_pk_mul_f32 v[8:9], v[2:3], v[8:9]
	v_pk_mul_f32 v[12:13], v[4:5], v[12:13]
	s_waitcnt vmcnt(1)
	v_lshlrev_b32_e32 v0, 16, v16
	v_and_b32_e32 v7, 0xffff0000, v16
	v_lshlrev_b32_e32 v14, 16, v17
	v_and_b32_e32 v15, 0xffff0000, v17
	v_mul_f32_e32 v16, 0xbfb8aa3b, v0
	v_mul_f32_e32 v17, 0xbfb8aa3b, v7
	v_mul_f32_e32 v20, 0xbfb8aa3b, v14
	v_mul_f32_e32 v27, 0xbfb8aa3b, v15
	v_exp_f32_e32 v16, v16
	v_exp_f32_e32 v17, v17
	v_exp_f32_e32 v20, v20
	v_exp_f32_e32 v27, v27
	v_add_f32_e32 v16, 1.0, v16
	v_add_f32_e32 v17, 1.0, v17
	v_add_f32_e32 v20, 1.0, v20
	v_add_f32_e32 v27, 1.0, v27
	v_rcp_f32_e32 v16, v16
	v_rcp_f32_e32 v17, v17
	v_rcp_f32_e32 v20, v20
	v_rcp_f32_e32 v27, v27
	v_mul_f32_e32 v0, v16, v0
	v_mul_f32_e32 v7, v17, v7
	v_mul_f32_e32 v14, v20, v14
	v_mul_f32_e32 v15, v27, v15
	v_mul_f32_e32 v0, v0, v8
	v_mul_f32_e32 v7, v7, v9
	v_mul_f32_e32 v8, v14, v12
	v_mul_f32_e32 v9, v15, v13
	v_cvt_pk_bf16_f32 v12, v0, v7
	v_cvt_pk_bf16_f32 v13, v8, v9
	v_mov_b64_e32 v[14:15], v[84:85]
	v_lshl_add_u32 v0, v6, 9, v22
	ds_read_b128 v[6:9], v0
	s_waitcnt lgkmcnt(0)
	v_pk_mul_f32 v[16:17], v[8:9], v[8:9]
	v_pk_mul_f32 v[18:19], v[6:7], v[6:7]
	s_nop 0
	v_pk_mov_b32 v[28:29], v[18:19], v[16:17] op_sel:[1,0]
	v_mov_b32_e32 v19, v17
	v_pk_add_f32 v[16:17], v[28:29], v[18:19]
	s_nop 0
	v_add_f32_e32 v0, v16, v17
	s_nop 1
	v_add_f32_dpp v0, v0, v0 quad_perm:[1,0,3,2] row_mask:0xf bank_mask:0xf
	s_nop 1
	v_add_f32_dpp v0, v0, v0 quad_perm:[2,3,0,1] row_mask:0xf bank_mask:0xf
	s_nop 1
	v_add_f32_dpp v0, v0, v0 row_half_mirror row_mask:0xf bank_mask:0xf
	s_nop 1
	v_add_co_u32_e64 v16, s[40:41], s4, v10
	v_add_co_u32_e32 v10, vcc, 0xb903000, v10
	v_add_f32_dpp v0, v0, v0 row_mirror row_mask:0xf bank_mask:0xf
	v_mov_b32_e32 v18, v0
	v_addc_co_u32_e64 v17, s[40:41], 0, v11, s[40:41]
	global_store_dwordx2 v[16:17], v[12:13], off offset:3072
	v_addc_co_u32_e32 v11, vcc, 0, v11, vcc
	s_nop 1
	v_permlane16_swap_b32_e32 v0, v18
	v_add_f32_e32 v0, v0, v18
	v_fmamk_f32 v0, v0, 0x3c000000, v216
	v_cmp_gt_f32_e64 s[40:41], s26, v0
	v_mul_f32_e32 v18, 0x4b800000, v0
	s_nop 0
	v_cndmask_b32_e64 v0, v0, v18, s[40:41]
	v_rsq_f32_e32 v0, v0
	s_nop 0
	v_mul_f32_e32 v12, 0x45800000, v0
	v_cndmask_b32_e64 v0, v0, v12, s[40:41]
	v_pk_mul_f32 v[6:7], v[6:7], v[0:1] op_sel_hi:[1,0]
	v_pk_mul_f32 v[8:9], v[8:9], v[0:1] op_sel_hi:[1,0]
	v_pk_mul_f32 v[2:3], v[2:3], v[6:7]
	v_pk_mul_f32 v[4:5], v[4:5], v[8:9]
	s_waitcnt vmcnt(1)
	v_lshlrev_b32_e32 v0, 16, v14
	v_and_b32_e32 v6, 0xffff0000, v14
	v_lshlrev_b32_e32 v7, 16, v15
	v_and_b32_e32 v8, 0xffff0000, v15
	v_mul_f32_e32 v9, 0xbfb8aa3b, v0
	v_mul_f32_e32 v12, 0xbfb8aa3b, v6
	v_mul_f32_e32 v13, 0xbfb8aa3b, v7
	v_mul_f32_e32 v14, 0xbfb8aa3b, v8
	v_exp_f32_e32 v9, v9
	v_exp_f32_e32 v12, v12
	v_exp_f32_e32 v13, v13
	v_exp_f32_e32 v14, v14
	v_add_f32_e32 v9, 1.0, v9
	v_add_f32_e32 v12, 1.0, v12
	v_add_f32_e32 v13, 1.0, v13
	v_add_f32_e32 v14, 1.0, v14
	v_rcp_f32_e32 v9, v9
	v_rcp_f32_e32 v12, v12
	v_rcp_f32_e32 v13, v13
	v_rcp_f32_e32 v14, v14
	v_mul_f32_e32 v0, v9, v0
	v_mul_f32_e32 v6, v12, v6
	v_mul_f32_e32 v7, v13, v7
	v_mul_f32_e32 v8, v14, v8
	v_mul_f32_e32 v0, v0, v2
	v_mul_f32_e32 v2, v6, v3
	v_mul_f32_e32 v3, v7, v4
	v_mul_f32_e32 v4, v8, v5
	v_cvt_pk_bf16_f32 v2, v0, v2
	v_cvt_pk_bf16_f32 v3, v3, v4
	global_store_dwordx2 v[10:11], v[2:3], off offset:3072
	s_branch .LBB0_70

; __device__ __forceinline__ unsigned cvt_pk_bf16(float lo, float hi) { unsigned r; asm volatile("v_cvt_pk_bf16_f32 %0, %1, %2" : "=v"(r) : "v"(lo), "v"(hi)); return r; }
; __device__ __forceinline__ void phase_norm(CArgs& a, int l, int which) {
;     ...
;         for (int u = 0; u < 2; ++u) { float ss = 0.f;
; #pragma unroll
;             for (int j = 0; j < 8; ++j) ss += (x[u][j].x * x[u][j].x + x[u][j].y * x[u][j].y) + (x[u][j].z * x[u][j].z + x[u][j].w * x[u][j].w);
;             const float rs = rsqrtf(wave_sum(ss) * (1.f / DM) + EPS);
;             if (!ok[u]) continue;
;             bf16_t* o = H + (size_t)(r0 + u * NGW) * DM;
; #pragma unroll
;             for (int j = 0; j < 8; ++j) { const int c = 4 * lane + 256 * j; const f32x4 g = *(const f32x4*)(gn + c), s1 = *(const f32x4*)(sc[u] + c), s0 = *(const f32x4*)(sh[u] + c);
;                 const f32x4 y = (x[u][j] * rs) * g * (1.f + s1) + s0;
;                 u32x2 w; w.x = cvt_pk_bf16(y.x, y.y); w.y = cvt_pk_bf16(y.z, y.w); *(u32x2*)(o + c) = w; } }
.LBB0_337:
	s_or_b64 exec, exec, s[20:21]
	v_cndmask_b32_e64 v99, v110, 4, s[40:41]
	s_waitcnt vmcnt(0)
	v_mul_f32_e32 v110, v63, v63
	v_mul_f32_e32 v111, v65, v65
	v_fmac_f32_e32 v110, v62, v62
	v_fmac_f32_e32 v111, v64, v64
	v_add_f32_e32 v110, v110, v111
	v_mul_f32_e32 v111, v59, v59
	v_mul_f32_e32 v113, v61, v61
	v_fmac_f32_e32 v111, v58, v58
	v_fmac_f32_e32 v113, v60, v60
	v_add_f32_e32 v111, v111, v113
	v_add_f32_e32 v110, v111, v110
	v_mul_f32_e32 v111, v51, v51
	v_mul_f32_e32 v113, v53, v53
	v_fmac_f32_e32 v111, v50, v50
	v_fmac_f32_e32 v113, v52, v52
	v_add_f32_e32 v111, v111, v113
	v_add_f32_e32 v110, v111, v110
	v_mul_f32_e32 v111, v43, v43
	v_mul_f32_e32 v113, v45, v45
	v_fmac_f32_e32 v111, v42, v42
	v_fmac_f32_e32 v113, v44, v44
	v_add_f32_e32 v111, v111, v113
	v_add_f32_e32 v110, v111, v110
	v_mul_f32_e32 v111, v35, v35
	v_mul_f32_e32 v113, v37, v37
	v_fmac_f32_e32 v111, v34, v34
	v_fmac_f32_e32 v113, v36, v36
	v_add_f32_e32 v111, v111, v113
	v_add_f32_e32 v110, v111, v110
	v_mul_f32_e32 v111, v27, v27
	v_mul_f32_e32 v113, v29, v29
	v_fmac_f32_e32 v111, v26, v26
	v_fmac_f32_e32 v113, v28, v28
	v_add_f32_e32 v111, v111, v113
	v_add_f32_e32 v110, v111, v110
	v_mul_f32_e32 v111, v19, v19
	v_mul_f32_e32 v113, v21, v21
	v_fmac_f32_e32 v111, v18, v18
	v_fmac_f32_e32 v113, v20, v20
	v_add_f32_e32 v111, v111, v113
	v_add_f32_e32 v110, v111, v110
	v_mul_f32_e32 v111, v11, v11
	v_mul_f32_e32 v113, v13, v13
	v_fmac_f32_e32 v111, v10, v10
	v_fmac_f32_e32 v113, v12, v12
	v_add_f32_e32 v111, v111, v113
	v_add_f32_e32 v110, v111, v110
	ds_bpermute_b32 v111, v69, v110
	s_and_b64 s[4:5], s[46:47], s[42:43]
	s_xor_b64 s[4:5], s[4:5], -1
	v_lshlrev_b32_e32 v124, 2, v84
	v_lshlrev_b32_e32 v122, 2, v86
	s_waitcnt lgkmcnt(0)
	v_add_f32_e32 v110, v110, v111
	ds_bpermute_b32 v111, v85, v110
	v_lshlrev_b32_e32 v120, 2, v88
	v_lshlrev_b32_e32 v118, 2, v90
	v_lshlrev_b32_e32 v116, 2, v94
	v_lshlrev_b32_e32 v114, 2, v98
	s_waitcnt lgkmcnt(0)
	v_add_f32_e32 v110, v110, v111
	s_nop 1
	v_add_f32_dpp v110, v110, v110 row_half_mirror row_mask:0xf bank_mask:0xf
	s_nop 1
	v_add_f32_dpp v110, v110, v110 row_mirror row_mask:0xf bank_mask:0xf
	v_mov_b32_e32 v111, v110
	s_nop 1
	v_permlane16_swap_b32_e32 v110, v111
	v_add_f32_e32 v111, v110, v111
	ds_bpermute_b32 v113, v95, v111
	v_lshlrev_b32_e32 v110, 2, v102
	s_and_saveexec_b64 s[20:21], s[4:5]
	s_cbranch_execz .LBB0_339
	v_mul_hi_i32_i24_e32 v127, 0xc000, v103
	v_mul_i32_i24_e32 v126, 0xc000, v103
	v_lshl_add_u64 v[126:127], s[72:73], 0, v[126:127]
	v_lshl_add_u64 v[128:129], v[126:127], 0, s[96:97]
	v_lshl_add_u64 v[132:133], v[128:129], 0, v[0:1]
	global_load_dwordx4 v[134:137], v[82:83], off
	global_load_dwordx4 v[138:141], v[132:133], off
	v_lshl_add_u64 v[132:133], v[126:127], 0, v[0:1]
	global_load_dwordx4 v[142:145], v[132:133], off
	s_waitcnt lgkmcnt(0)
	v_add_f32_e32 v103, v111, v113
	v_fmamk_f32 v103, v103, 0x3a000000, v216
	v_cmp_gt_f32_e32 vcc, s26, v103
	v_mul_f32_e32 v111, 0x4b800000, v103
	v_lshlrev_b64 v[146:147], 12, v[66:67]
	v_cndmask_b32_e32 v103, v103, v111, vcc
	v_rsq_f32_e32 v103, v103
	v_mov_b32_e32 v125, v1
	v_mov_b32_e32 v123, v1
	v_mov_b32_e32 v121, v1
	v_mul_f32_e32 v111, 0x45800000, v103
	v_cndmask_b32_e32 v130, v103, v111, vcc
	v_pk_mul_f32 v[64:65], v[64:65], v[130:131] op_sel_hi:[1,0]
	v_pk_mul_f32 v[62:63], v[62:63], v[130:131] op_sel_hi:[1,0]
	v_pk_mul_f32 v[58:59], v[58:59], v[130:131] op_sel_hi:[1,0]
	v_pk_mul_f32 v[60:61], v[60:61], v[130:131] op_sel_hi:[1,0]
	v_pk_mul_f32 v[52:53], v[52:53], v[130:131] op_sel_hi:[1,0]
	v_pk_mul_f32 v[50:51], v[50:51], v[130:131] op_sel_hi:[1,0]
	v_pk_mul_f32 v[44:45], v[44:45], v[130:131] op_sel_hi:[1,0]
	v_pk_mul_f32 v[42:43], v[42:43], v[130:131] op_sel_hi:[1,0]
	v_mov_b32_e32 v119, v1
	v_pk_mul_f32 v[36:37], v[36:37], v[130:131] op_sel_hi:[1,0]
	v_pk_mul_f32 v[34:35], v[34:35], v[130:131] op_sel_hi:[1,0]
	v_mov_b32_e32 v117, v1
	v_pk_mul_f32 v[28:29], v[28:29], v[130:131] op_sel_hi:[1,0]
	v_pk_mul_f32 v[26:27], v[26:27], v[130:131] op_sel_hi:[1,0]
	v_mov_b32_e32 v115, v1
	v_pk_mul_f32 v[20:21], v[20:21], v[130:131] op_sel_hi:[1,0]
	v_pk_mul_f32 v[18:19], v[18:19], v[130:131] op_sel_hi:[1,0]
	v_mov_b32_e32 v111, v1
	v_pk_mul_f32 v[12:13], v[12:13], v[130:131] op_sel_hi:[1,0]
	v_pk_mul_f32 v[10:11], v[10:11], v[130:131] op_sel_hi:[1,0]
	s_waitcnt vmcnt(2)
	v_pk_mul_f32 v[62:63], v[62:63], v[134:135]
	v_pk_mul_f32 v[64:65], v[64:65], v[136:137]
	s_waitcnt vmcnt(1)
	v_pk_add_f32 v[136:137], v[138:139], 1.0 op_sel_hi:[1,0]
	v_pk_add_f32 v[134:135], v[140:141], 1.0 op_sel_hi:[1,0]
	s_waitcnt vmcnt(0)
	v_pk_fma_f32 v[62:63], v[62:63], v[136:137], v[142:143]
	v_pk_fma_f32 v[64:65], v[64:65], v[134:135], v[144:145]
	v_cvt_pk_bf16_f32 v134, v62, v63
	v_lshl_add_u64 v[62:63], v[106:107], 0, v[146:147]
	v_cvt_pk_bf16_f32 v135, v64, v65
	global_store_dwordx2 v[62:63], v[134:135], off
	global_load_dwordx4 v[134:137], v[82:83], off offset:1024
	v_lshl_add_u64 v[64:65], v[128:129], 0, v[124:125]
	global_load_dwordx4 v[138:141], v[64:65], off
	global_load_dwordx4 v[142:145], v[132:133], off offset:1024
	s_waitcnt vmcnt(2)
; __device__ __forceinline__ unsigned cvt_pk_bf16(float lo, float hi) { unsigned r; asm volatile("v_cvt_pk_bf16_f32 %0, %1, %2" : "=v"(r) : "v"(lo), "v"(hi)); return r; }
; __device__ __forceinline__ void phase_norm(CArgs& a, int l, int which) {
;     ...
; #pragma unroll
;             for (int j = 0; j < 8; ++j) { const int c = 4 * lane + 256 * j; const f32x4 g = *(const f32x4*)(gn + c), s1 = *(const f32x4*)(sc[u] + c), s0 = *(const f32x4*)(sh[u] + c);
;                 const f32x4 y = (x[u][j] * rs) * g * (1.f + s1) + s0;
;                 u32x2 w; w.x = cvt_pk_bf16(y.x, y.y); w.y = cvt_pk_bf16(y.z, y.w); *(u32x2*)(o + c) = w; } }
	v_pk_mul_f32 v[58:59], v[58:59], v[134:135]
	s_waitcnt vmcnt(1)
	v_pk_add_f32 v[134:135], v[138:139], 1.0 op_sel_hi:[1,0]
	v_pk_mul_f32 v[60:61], v[60:61], v[136:137]
	v_pk_add_f32 v[64:65], v[140:141], 1.0 op_sel_hi:[1,0]
	s_waitcnt vmcnt(0)
	v_pk_fma_f32 v[58:59], v[58:59], v[134:135], v[142:143]
	v_pk_fma_f32 v[60:61], v[60:61], v[64:65], v[144:145]
	v_cvt_pk_bf16_f32 v58, v58, v59
	v_lshl_add_u64 v[64:65], v[128:129], 0, v[122:123]
	v_cvt_pk_bf16_f32 v59, v60, v61
	global_store_dwordx2 v[62:63], v[58:59], off offset:512
	global_load_dwordx4 v[58:61], v[82:83], off offset:2048
	s_nop 0
	global_load_dwordx4 v[134:137], v[64:65], off
	global_load_dwordx4 v[138:141], v[132:133], off offset:2048
	s_waitcnt vmcnt(2)
	v_pk_mul_f32 v[50:51], v[50:51], v[58:59]
	v_pk_mul_f32 v[52:53], v[52:53], v[60:61]
	s_waitcnt vmcnt(1)
	v_pk_add_f32 v[60:61], v[134:135], 1.0 op_sel_hi:[1,0]
	v_pk_add_f32 v[58:59], v[136:137], 1.0 op_sel_hi:[1,0]
	s_waitcnt vmcnt(0)
	v_pk_fma_f32 v[50:51], v[50:51], v[60:61], v[138:139]
	v_pk_fma_f32 v[52:53], v[52:53], v[58:59], v[140:141]
	v_cvt_pk_bf16_f32 v50, v50, v51
	v_lshl_add_u64 v[58:59], v[128:129], 0, v[120:121]
	v_cvt_pk_bf16_f32 v51, v52, v53
	global_store_dwordx2 v[62:63], v[50:51], off offset:1024
	global_load_dwordx4 v[50:53], v[82:83], off offset:3072
	s_nop 0
	global_load_dwordx4 v[58:61], v[58:59], off
	s_nop 0
	global_load_dwordx4 v[132:135], v[132:133], off offset:3072
	s_waitcnt vmcnt(2)
	v_pk_mul_f32 v[42:43], v[42:43], v[50:51]
	v_pk_mul_f32 v[44:45], v[44:45], v[52:53]
	s_waitcnt vmcnt(1)
	v_pk_add_f32 v[52:53], v[58:59], 1.0 op_sel_hi:[1,0]
	v_pk_add_f32 v[50:51], v[60:61], 1.0 op_sel_hi:[1,0]
	s_waitcnt vmcnt(0)
	v_pk_fma_f32 v[42:43], v[42:43], v[52:53], v[132:133]
	v_pk_fma_f32 v[44:45], v[44:45], v[50:51], v[134:135]
	v_cvt_pk_bf16_f32 v42, v42, v43
	v_lshl_add_u64 v[50:51], v[128:129], 0, v[118:119]
	v_cvt_pk_bf16_f32 v43, v44, v45
	global_store_dwordx2 v[62:63], v[42:43], off offset:1536
	global_load_dwordx4 v[42:45], v[92:93], off
	v_lshl_add_u64 v[58:59], v[126:127], 0, v[118:119]
	global_load_dwordx4 v[50:53], v[50:51], off
	s_waitcnt vmcnt(1)
	v_pk_mul_f32 v[34:35], v[34:35], v[42:43]
	global_load_dwordx4 v[58:61], v[58:59], off
	v_pk_mul_f32 v[36:37], v[36:37], v[44:45]
	s_waitcnt vmcnt(1)
	v_pk_add_f32 v[44:45], v[50:51], 1.0 op_sel_hi:[1,0]
	v_pk_add_f32 v[42:43], v[52:53], 1.0 op_sel_hi:[1,0]
	v_lshl_add_u64 v[50:51], v[126:127], 0, v[116:117]
	s_waitcnt vmcnt(0)
	v_pk_fma_f32 v[34:35], v[34:35], v[44:45], v[58:59]
	v_pk_fma_f32 v[36:37], v[36:37], v[42:43], v[60:61]
	v_cvt_pk_bf16_f32 v34, v34, v35
	v_lshl_add_u64 v[42:43], v[128:129], 0, v[116:117]
	v_cvt_pk_bf16_f32 v35, v36, v37
	global_store_dwordx2 v[62:63], v[34:35], off offset:2048
	global_load_dwordx4 v[34:37], v[96:97], off
	s_waitcnt vmcnt(0)
	v_pk_mul_f32 v[26:27], v[26:27], v[34:35]
	global_load_dwordx4 v[42:45], v[42:43], off
	v_pk_mul_f32 v[28:29], v[28:29], v[36:37]
	global_load_dwordx4 v[50:53], v[50:51], off
	s_waitcnt vmcnt(1)
	v_pk_add_f32 v[36:37], v[42:43], 1.0 op_sel_hi:[1,0]
	v_pk_add_f32 v[34:35], v[44:45], 1.0 op_sel_hi:[1,0]
	s_waitcnt vmcnt(0)
	v_pk_fma_f32 v[26:27], v[26:27], v[36:37], v[50:51]
	v_pk_fma_f32 v[28:29], v[28:29], v[34:35], v[52:53]
	v_cvt_pk_bf16_f32 v26, v26, v27
	v_lshl_add_u64 v[34:35], v[128:129], 0, v[114:115]
	v_cvt_pk_bf16_f32 v27, v28, v29
	global_store_dwordx2 v[62:63], v[26:27], off offset:2560
	global_load_dwordx4 v[26:29], v[100:101], off
	v_lshl_add_u64 v[42:43], v[126:127], 0, v[114:115]
	global_load_dwordx4 v[34:37], v[34:35], off
	s_waitcnt vmcnt(1)
	v_pk_mul_f32 v[18:19], v[18:19], v[26:27]
	global_load_dwordx4 v[42:45], v[42:43], off
	v_pk_mul_f32 v[20:21], v[20:21], v[28:29]
	s_waitcnt vmcnt(1)
	v_pk_add_f32 v[28:29], v[34:35], 1.0 op_sel_hi:[1,0]
	v_pk_add_f32 v[26:27], v[36:37], 1.0 op_sel_hi:[1,0]
	v_lshl_add_u64 v[34:35], v[126:127], 0, v[110:111]
	s_waitcnt vmcnt(0)
	v_pk_fma_f32 v[18:19], v[18:19], v[28:29], v[42:43]
	v_pk_fma_f32 v[20:21], v[20:21], v[26:27], v[44:45]
	v_cvt_pk_bf16_f32 v18, v18, v19
	v_lshl_add_u64 v[26:27], v[128:129], 0, v[110:111]
	v_cvt_pk_bf16_f32 v19, v20, v21
	global_store_dwordx2 v[62:63], v[18:19], off offset:3072
	global_load_dwordx4 v[18:21], v[104:105], off
	s_waitcnt vmcnt(0)
	v_pk_mul_f32 v[10:11], v[10:11], v[18:19]
	global_load_dwordx4 v[26:29], v[26:27], off
	v_pk_mul_f32 v[12:13], v[12:13], v[20:21]
	global_load_dwordx4 v[34:37], v[34:35], off
	s_waitcnt vmcnt(1)
	v_pk_add_f32 v[20:21], v[26:27], 1.0 op_sel_hi:[1,0]
	v_pk_add_f32 v[18:19], v[28:29], 1.0 op_sel_hi:[1,0]
	s_waitcnt vmcnt(0)
	v_pk_fma_f32 v[10:11], v[10:11], v[20:21], v[34:35]
	v_pk_fma_f32 v[12:13], v[12:13], v[18:19], v[36:37]
	v_cvt_pk_bf16_f32 v10, v10, v11
	s_nop 0
	v_cvt_pk_bf16_f32 v11, v12, v13
	global_store_dwordx2 v[62:63], v[10:11], off offset:3584
